# v18 + start delays for slack blocks in FFN-in (light blocks 128..255, s_sleep 96) and gMLP in-proj (blocks 0..127, s_sleep 127) phases
# baseline (speedup 1.0000x reference)
.LBB0_203:
	s_lshr_b32 s6, s4, 1
	v_writelane_b32 v255, s6, 19
	s_nop 1
	v_writelane_b32 v255, s7, 20
	v_writelane_b32 v255, s4, 21
	s_bitcmp1_b32 s4, 0
	s_nop 0
	v_writelane_b32 v255, s5, 22
	s_cselect_b64 s[4:5], -1, 0
	s_and_b64 vcc, exec, s[4:5]
	s_mov_b64 s[4:5], -1
	s_cbranch_vccz .LBB0_385
	s_cmpk_lt_u32 s2, 0x80
	s_cbranch_scc0 .Lg3_nodelay
	s_sleep 127
.Lg3_nodelay:
	s_mov_b64 s[4:5], s[24:25]
	s_add_u32 s6, s4, 0xc50c000
	s_addc_u32 s7, s5, 0

.LBB0_1091:
	s_andn2_b64 vcc, exec, s[4:5]
	s_cbranch_vccnz .LBB0_1158
	s_cmpk_ge_u32 s2, 0x80
	s_cbranch_scc0 .Lg2_nodelay
	s_sleep 96
.Lg2_nodelay:
	s_mov_b64 s[28:29], s[24:25]
	s_add_u32 s42, s28, 0xc308000
	s_addc_u32 s43, s29, 0
